# scanC output normalisation: the two 3-hop row reductions use DPP quad_perm / row_half_mirror adds (same partners and order) instead of ds_bpermute_b32 round trips
# speedup vs baseline: 1.0049x; 1.0010x over previous
; __device__ __forceinline__ bf16_t f2bf(float f) { return (bf16_t)(pk2(f, 0.f) & 0xffffu); }
; __device__ void scanC_phase(const Params& p, int l, bool last, char* shm, int w0) {
;     ...
; #pragma unroll
;       for (int j = 0; j < 4; ++j) {
;         const int t = tt * 16 + fq * 4 + j, s = ts * 16 + fr;
;         const float v = (s <= t ? af[j] : 0.f) + (s >= t ? ab[j] : 0.f);
;         ATT[t * SSTR + s] = f2bf(v);
;       }
;     }
;     __syncthreads();
; #pragma unroll
;     for (int q = 0; q < 2; ++q) {
;       const int id = wv * 2 + q, tt = id >> 2, et = id & 3;
;       f32x4 acc = {0.f, 0.f, 0.f, 0.f};
; #pragma unroll
;       for (int ks = 0; ks < 2; ++ks) {
;         acc = mma16(ATT + tt * 16 * SSTR + ks * 32, VT + et * 16 * SSTR + ks * 32, acc, fr, fq);
;         acc = mma16(QFB + tt * 16 * SSTR + ks * 32, ST + et * 16 * SSTR + ks * 32, acc, fr, fq);
;       }
; #pragma unroll
;       for (int j = 0; j < 4; ++j) O[(tt * 16 + fq * 4 + j) * 65 + et * 16 + fr] = acc[j];
;     }
;     __syncthreads();
;     { const int t = tid >> 3, e0 = (tid & 7) * 8; float o[8]; float s = 0.f;
; #pragma unroll
;       for (int j = 0; j < 8; ++j) { o[j] = O[t * 65 + e0 + j]; s += o[j]; }
;       s += __shfl_xor(s, 1); s += __shfl_xor(s, 2); s += __shfl_xor(s, 4);
;       const float mu = mx == 1 ? s * (1.f / 64.f) : 0.f; float qq = 0.f;
; #pragma unroll
;       for (int j = 0; j < 8; ++j) { o[j] -= mu; qq += o[j] * o[j]; }
;       qq += __shfl_xor(qq, 1); qq += __shfl_xor(qq, 2); qq += __shfl_xor(qq, 4);
;       const float rs = rsqrtf(qq * (1.f / 64.f) + EPS);
.LBB0_785:
	s_or_b64 exec, exec, s[6:7]
	v_readlane_b32 s6, v255, 19
	v_readlane_b32 s7, v255, 20
	v_cndmask_b32_e64 v0, v30, 0, s[66:67]
	s_mov_b32 s2, 0x800000
	s_nop 2
	v_cndmask_b32_e64 v26, v26, 0, s[6:7]
	v_add_f32_e32 v0, v0, v26
	v_readlane_b32 s6, v255, 21
	v_cvt_pk_bf16_f32 v0, v0, s0
	v_readlane_b32 s7, v255, 22
	ds_write_b16 v103, v0 offset:63488
	v_cndmask_b32_e64 v26, 0, v27, s[66:67]
	v_cndmask_b32_e64 v0, v31, 0, s[6:7]
	v_add_f32_e32 v0, v0, v26
	v_readlane_b32 s6, v255, 23
	v_cvt_pk_bf16_f32 v0, v0, s0
	v_readlane_b32 s7, v255, 24
	ds_write_b16 v103, v0 offset:63632
	s_nop 0
	v_cndmask_b32_e64 v0, v32, 0, s[6:7]
	v_readlane_b32 s6, v255, 25
	v_readlane_b32 s7, v255, 26
	s_nop 1
	v_cndmask_b32_e64 v26, v28, 0, s[6:7]
	v_add_f32_e32 v0, v0, v26
	v_readlane_b32 s6, v255, 27
	v_cvt_pk_bf16_f32 v0, v0, s0
	v_readlane_b32 s7, v255, 28
	ds_write_b16 v103, v0 offset:63776
	v_cndmask_b32_e64 v26, v29, 0, s[42:43]
	v_cndmask_b32_e64 v0, v33, 0, s[6:7]
	v_add_f32_e32 v0, v0, v26
	v_cvt_pk_bf16_f32 v0, v0, s0
	ds_write_b16 v103, v0 offset:63920
	s_waitcnt lgkmcnt(0)
	s_barrier
	ds_read_b128 v[26:29], v68 offset:63488
	ds_read_b128 v[30:33], v96 offset:26624
	s_waitcnt lgkmcnt(0)
	v_mfma_f32_16x16x32_bf16 v[26:29], v[26:29], v[30:33], 0
	ds_read_b128 v[30:33], v68 offset:35840
	ds_read_b128 v[108:111], v96 offset:54272
	s_waitcnt lgkmcnt(0)
	v_mfma_f32_16x16x32_bf16 v[26:29], v[30:33], v[108:111], v[26:29]
	ds_read_b128 v[30:33], v68 offset:63552
	ds_read_b128 v[108:111], v96 offset:26688
	s_waitcnt lgkmcnt(0)
	v_mfma_f32_16x16x32_bf16 v[26:29], v[30:33], v[108:111], v[26:29]
	ds_read_b128 v[30:33], v68 offset:35904
	ds_read_b128 v[108:111], v96 offset:54336
	s_waitcnt lgkmcnt(0)
	v_mfma_f32_16x16x32_bf16 v[26:29], v[30:33], v[108:111], v[26:29]
	s_nop 7
	ds_write2_b32 v104, v26, v27 offset1:65
	ds_write2_b32 v104, v28, v29 offset0:130 offset1:195
	ds_read_b128 v[26:29], v68 offset:63488
	ds_read_b128 v[30:33], v97 offset:26624
	s_waitcnt lgkmcnt(0)
	v_mfma_f32_16x16x32_bf16 v[26:29], v[26:29], v[30:33], 0
	ds_read_b128 v[30:33], v68 offset:35840
	ds_read_b128 v[108:111], v97 offset:54272
	s_waitcnt lgkmcnt(0)
	v_mfma_f32_16x16x32_bf16 v[26:29], v[30:33], v[108:111], v[26:29]
	ds_read_b128 v[30:33], v68 offset:63552
	ds_read_b128 v[108:111], v97 offset:26688
	s_waitcnt lgkmcnt(0)
	v_mfma_f32_16x16x32_bf16 v[26:29], v[30:33], v[108:111], v[26:29]
	ds_read_b128 v[30:33], v68 offset:35904
	ds_read_b128 v[108:111], v97 offset:54336
	s_waitcnt lgkmcnt(0)
	v_mfma_f32_16x16x32_bf16 v[26:29], v[30:33], v[108:111], v[26:29]
	s_nop 7
	ds_write2_b32 v105, v26, v27 offset1:65
	ds_write2_b32 v105, v28, v29 offset0:130 offset1:195
	s_waitcnt lgkmcnt(0)
	s_barrier
	ds_read2_b32 v[26:27], v69 offset0:6 offset1:7
	ds_read2_b32 v[28:29], v69 offset0:4 offset1:5
	ds_read2_b32 v[30:31], v69 offset0:2 offset1:3
	ds_read2_b32 v[32:33], v69 offset1:1
	s_waitcnt lgkmcnt(0)
	v_add_f32_e32 v0, 0, v32
	v_add_f32_e32 v0, v0, v33
	v_add_f32_e32 v0, v0, v30
	v_add_f32_e32 v0, v0, v31
	v_add_f32_e32 v0, v0, v28
	v_add_f32_e32 v0, v0, v29
	v_add_f32_e32 v0, v0, v26
	v_add_f32_e32 v0, v0, v27
	s_nop 1
	v_add_f32_dpp v0, v0, v0 quad_perm:[1,0,3,2] row_mask:0xf bank_mask:0xf
	s_nop 1
	v_add_f32_dpp v0, v0, v0 quad_perm:[2,3,0,1] row_mask:0xf bank_mask:0xf
	s_nop 1
	v_add_f32_dpp v0, v0, v0 row_half_mirror row_mask:0xf bank_mask:0xf
	v_mul_f32_e32 v0, 0x3c800000, v0
	v_cndmask_b32_e64 v0, 0, v0, s[80:81]
	v_pk_add_f32 v[32:33], v[32:33], v[0:1] op_sel_hi:[1,0] neg_lo:[0,1] neg_hi:[0,1]
	v_pk_add_f32 v[30:31], v[30:31], v[0:1] op_sel_hi:[1,0] neg_lo:[0,1] neg_hi:[0,1]
	v_pk_mul_f32 v[34:35], v[32:33], v[32:33]
	v_pk_mul_f32 v[84:85], v[30:31], v[30:31]
	v_pk_add_f32 v[28:29], v[28:29], v[0:1] op_sel_hi:[1,0] neg_lo:[0,1] neg_hi:[0,1]
	v_pk_add_f32 v[26:27], v[26:27], v[0:1] op_sel_hi:[1,0] neg_lo:[0,1] neg_hi:[0,1]
	v_add_f32_e32 v0, v34, v35
	v_add_f32_e32 v0, v84, v0
	v_pk_mul_f32 v[108:109], v[28:29], v[28:29]
	v_add_f32_e32 v0, v85, v0
	v_add_f32_e32 v0, v108, v0
	v_pk_mul_f32 v[110:111], v[26:27], v[26:27]
	v_add_f32_e32 v0, v109, v0
	v_add_f32_e32 v0, v110, v0
	v_add_f32_e32 v0, v111, v0
	s_nop 1
	v_add_f32_dpp v0, v0, v0 quad_perm:[1,0,3,2] row_mask:0xf bank_mask:0xf
	s_nop 1
	v_add_f32_dpp v0, v0, v0 quad_perm:[2,3,0,1] row_mask:0xf bank_mask:0xf
	s_nop 1
	v_add_f32_dpp v0, v0, v0 row_half_mirror row_mask:0xf bank_mask:0xf
	v_mov_b32_e32 v34, 0x358637bd
	v_fmamk_f32 v0, v0, 0x3c800000, v34
	v_cmp_gt_f32_e32 vcc, s2, v0
	v_mul_f32_e32 v34, 0x4b800000, v0
	s_nop 0
	v_cndmask_b32_e32 v0, v0, v34, vcc
	v_rsq_f32_e32 v0, v0
	s_nop 0
	v_mul_f32_e32 v34, 0x45800000, v0
	v_cndmask_b32_e32 v34, v0, v34, vcc
	v_mul_f32_e32 v0, v32, v34
	v_cndmask_b32_e64 v32, 0, 1, s[12:13]
	v_cmp_ne_u32_e64 s[80:81], 1, v32
	s_andn2_b64 vcc, exec, s[12:13]
	s_cbranch_vccnz .LBB0_809
	v_mov_b32_e32 v32, v176
	v_mul_f32_e32 v0, v0, v32
	s_and_b64 vcc, exec, s[80:81]
	v_mul_f32_e32 v32, v33, v34
	s_cbranch_vccz .LBB0_810
